# P4 sample-row small-tile GEMM: all fragment loads of the K step in flight together
# baseline (speedup 1.0000x reference)
.LBB0_707:
	s_lshl_b32 s14, s16, 2
	s_andn2_b32 s14, s14, 63
	s_addk_i32 s14, 0x4000
	s_lshl_b32 s15, s16, 6
	v_add_u32_e32 v76, s14, v113
	s_and_b32 s18, s15, 0x3c0
	v_ashrrev_i32_e32 v77, 31, v76
	v_or_b32_e32 v2, s18, v114
	v_lshlrev_b64 v[0:1], 11, v[76:77]
	v_lshl_add_u64 v[0:1], s[36:37], 0, v[0:1]
	v_lshlrev_b32_e32 v194, 1, v2
	v_lshl_add_u64 v[78:79], v[0:1], 0, v[194:195]
	global_load_dwordx4 v[0:3], v[78:79], off
	s_andn2_b64 vcc, exec, s[8:9]
	s_cbranch_vccnz .LBB0_710
	s_and_b32 s14, s7, 0x3c0
	v_or_b32_e32 v4, s14, v112
	v_lshlrev_b32_e32 v5, 1, v4
	v_or_b32_e32 v6, 32, v5
	v_mad_i64_i32 v[80:81], s[14:15], s4, v6, v[70:71]
	v_or_b32_e32 v6, 0x60, v5
	v_or_b32_e32 v5, 64, v5
	v_mad_i64_i32 v[82:83], s[14:15], s4, v6, v[72:73]
	v_mad_i64_i32 v[84:85], s[14:15], s4, v5, v[72:73]
	v_mad_u64_u32 v[86:87], s[14:15], s10, v4, v[72:73]
	s_and_b32 s14, s6, 0xffffffc0
	v_mad_i32_i24 v87, s11, v4, v87
	v_add_u32_e32 v4, s14, v125
	v_ashrrev_i32_e32 v5, 31, v4
	v_mul_lo_u32 v6, s10, v5
	v_mul_lo_u32 v7, s11, v4
	v_mad_u64_u32 v[88:89], s[14:15], s10, v4, v[74:75]
	v_lshlrev_b64 v[4:5], 1, v[4:5]
	v_add3_u32 v89, v7, v89, v6
	v_lshl_add_u64 v[6:7], v[4:5], 0, s[42:43]
	v_mul_lo_u32 v7, s4, v7
	v_mul_lo_u32 v8, s5, v6
	v_mad_u64_u32 v[90:91], s[14:15], s4, v6, v[74:75]
	v_add3_u32 v91, v8, v91, v7
	v_lshl_add_u64 v[6:7], v[4:5], 0, 32
	v_lshl_add_u64 v[4:5], v[4:5], 0, 64
	v_mul_lo_u32 v7, s4, v7
	v_mul_lo_u32 v8, s5, v6
	v_mad_u64_u32 v[92:93], s[14:15], s4, v6, v[74:75]
	v_mul_lo_u32 v5, s4, v5
	v_mul_lo_u32 v6, s5, v4
	v_mad_u64_u32 v[94:95], s[14:15], s4, v4, v[74:75]
	v_mov_b32_e32 v12, 0
	v_add3_u32 v93, v8, v93, v7
	v_add3_u32 v95, v6, v95, v5
	s_mov_b32 s14, 0
	v_mov_b32_e32 v13, v12
	v_mov_b32_e32 v14, v12
	v_mov_b32_e32 v15, v12
	v_mov_b32_e32 v36, v12
	v_mov_b32_e32 v37, v12
	v_mov_b32_e32 v38, v12
	v_mov_b32_e32 v39, v12
	v_mov_b32_e32 v40, v12
	v_mov_b32_e32 v41, v12
	v_mov_b32_e32 v42, v12
	v_mov_b32_e32 v43, v12
	v_mov_b32_e32 v44, v12
	v_mov_b32_e32 v45, v12
	v_mov_b32_e32 v46, v12
	v_mov_b32_e32 v47, v12
	v_mov_b32_e32 v48, v12
	v_mov_b32_e32 v49, v12
	v_mov_b32_e32 v50, v12
	v_mov_b32_e32 v51, v12
	v_mov_b32_e32 v28, v12
	v_mov_b32_e32 v29, v12
	v_mov_b32_e32 v30, v12
	v_mov_b32_e32 v31, v12
	v_mov_b32_e32 v20, v12
	v_mov_b32_e32 v21, v12
	v_mov_b32_e32 v22, v12
	v_mov_b32_e32 v23, v12
	v_mov_b32_e32 v8, v12
	v_mov_b32_e32 v9, v12
	v_mov_b32_e32 v10, v12
	v_mov_b32_e32 v11, v12
	v_mov_b32_e32 v32, v12
	v_mov_b32_e32 v33, v12
	v_mov_b32_e32 v34, v12
	v_mov_b32_e32 v35, v12
	v_mov_b32_e32 v24, v12
	v_mov_b32_e32 v25, v12
	v_mov_b32_e32 v26, v12
	v_mov_b32_e32 v27, v12
	v_mov_b32_e32 v16, v12
	v_mov_b32_e32 v17, v12
	v_mov_b32_e32 v18, v12
	v_mov_b32_e32 v19, v12
	v_mov_b32_e32 v4, v12
	v_mov_b32_e32 v5, v12
	v_mov_b32_e32 v6, v12
	v_mov_b32_e32 v7, v12
	v_mov_b32_e32 v60, v12
	v_mov_b32_e32 v61, v12
	v_mov_b32_e32 v62, v12
	v_mov_b32_e32 v63, v12
	v_mov_b32_e32 v56, v12
	v_mov_b32_e32 v57, v12
	v_mov_b32_e32 v58, v12
	v_mov_b32_e32 v59, v12
	v_mov_b32_e32 v64, v12
	v_mov_b32_e32 v65, v12
	v_mov_b32_e32 v66, v12
	v_mov_b32_e32 v67, v12
	v_mov_b32_e32 v52, v12
	v_mov_b32_e32 v53, v12
	v_mov_b32_e32 v54, v12
	v_mov_b32_e32 v55, v12
	s_cmpk_lg_i32 s3, 0x80
	s_cbranch_scc1 .LBB0_709
	v_lshl_add_u64 v[110:111], v[86:87], 0, v[68:69]
	v_lshl_add_u64 v[108:109], v[80:81], 0, v[68:69]
	v_lshl_add_u64 v[104:105], v[84:85], 0, v[68:69]
	v_lshl_add_u64 v[102:103], v[82:83], 0, v[68:69]
	v_lshl_add_u64 v[106:107], v[88:89], 0, v[68:69]
	v_lshl_add_u64 v[98:99], v[92:93], 0, v[68:69]
	v_lshl_add_u64 v[100:101], v[94:95], 0, v[68:69]
	v_lshl_add_u64 v[96:97], v[90:91], 0, v[68:69]
	global_load_dwordx4 v[130:133], v[110:111], off
	global_load_dwordx4 v[134:137], v[108:109], off offset:-128
	global_load_dwordx4 v[138:141], v[104:105], off
	global_load_dwordx4 v[142:145], v[102:103], off
	global_load_dwordx4 v[146:149], v[106:107], off offset:-128
	global_load_dwordx4 v[150:153], v[98:99], off offset:-128
	global_load_dwordx4 v[154:157], v[100:101], off offset:-128
	global_load_dwordx4 v[158:161], v[96:97], off offset:-128
	global_load_dwordx4 v[162:165], v[110:111], off offset:16
	global_load_dwordx4 v[166:169], v[108:109], off offset:-112
	global_load_dwordx4 v[170:173], v[104:105], off offset:16
	global_load_dwordx4 v[174:177], v[102:103], off offset:16
	global_load_dwordx4 v[178:181], v[106:107], off offset:-112
	global_load_dwordx4 v[182:185], v[98:99], off offset:-112
	global_load_dwordx4 v[186:189], v[100:101], off offset:-112
	global_load_dwordx4 v[198:201], v[96:97], off offset:-112
	global_load_dwordx4 v[218:221], v[110:111], off offset:128
	global_load_dwordx4 v[222:225], v[108:109], off
	global_load_dwordx4 v[226:229], v[104:105], off offset:128
	global_load_dwordx4 v[230:233], v[102:103], off offset:128
	global_load_dwordx4 v[234:237], v[106:107], off
	global_load_dwordx4 v[238:241], v[98:99], off
	global_load_dwordx4 v[246:249], v[100:101], off
	s_waitcnt vmcnt(18)
	v_mfma_f32_16x16x32_bf16 v[12:15], v[130:133], v[146:149], v[12:15]
	s_waitcnt vmcnt(18)
	v_mfma_f32_16x16x32_bf16 v[36:39], v[134:137], v[146:149], v[36:39]
	s_waitcnt vmcnt(18)
	v_mfma_f32_16x16x32_bf16 v[40:43], v[138:141], v[146:149], v[40:43]
	s_waitcnt vmcnt(18)
	v_mfma_f32_16x16x32_bf16 v[44:47], v[142:145], v[146:149], v[44:47]
	global_load_dwordx4 v[146:149], v[96:97], off
	s_waitcnt vmcnt(18)
	v_mfma_f32_16x16x32_bf16 v[48:51], v[130:133], v[150:153], v[48:51]
	v_mfma_f32_16x16x32_bf16 v[28:31], v[134:137], v[150:153], v[28:31]
	v_mfma_f32_16x16x32_bf16 v[20:23], v[138:141], v[150:153], v[20:23]
	v_mfma_f32_16x16x32_bf16 v[8:11], v[142:145], v[150:153], v[8:11]
	global_load_dwordx4 v[150:153], v[110:111], off offset:144
	s_waitcnt vmcnt(18)
	v_mfma_f32_16x16x32_bf16 v[32:35], v[130:133], v[154:157], v[32:35]
	v_mfma_f32_16x16x32_bf16 v[24:27], v[134:137], v[154:157], v[24:27]
	v_mfma_f32_16x16x32_bf16 v[16:19], v[138:141], v[154:157], v[16:19]
	v_mfma_f32_16x16x32_bf16 v[4:7], v[142:145], v[154:157], v[4:7]
	global_load_dwordx4 v[154:157], v[108:109], off offset:16
	s_waitcnt vmcnt(18)
	v_mfma_f32_16x16x32_bf16 v[60:63], v[130:133], v[158:161], v[60:63]
	global_load_dwordx4 v[130:133], v[104:105], off offset:144
	v_mfma_f32_16x16x32_bf16 v[56:59], v[134:137], v[158:161], v[56:59]
	global_load_dwordx4 v[134:137], v[102:103], off offset:144
	v_mfma_f32_16x16x32_bf16 v[64:67], v[138:141], v[158:161], v[64:67]
	global_load_dwordx4 v[138:141], v[106:107], off offset:16
	v_mfma_f32_16x16x32_bf16 v[52:55], v[142:145], v[158:161], v[52:55]
	global_load_dwordx4 v[142:145], v[98:99], off offset:16
	global_load_dwordx4 v[158:161], v[100:101], off offset:16
	s_waitcnt vmcnt(18)
	v_mfma_f32_16x16x32_bf16 v[12:15], v[162:165], v[178:181], v[12:15]
	s_waitcnt vmcnt(18)
	v_mfma_f32_16x16x32_bf16 v[36:39], v[166:169], v[178:181], v[36:39]
	s_waitcnt vmcnt(18)
	v_mfma_f32_16x16x32_bf16 v[40:43], v[170:173], v[178:181], v[40:43]
	s_waitcnt vmcnt(18)
	v_mfma_f32_16x16x32_bf16 v[44:47], v[174:177], v[178:181], v[44:47]
	global_load_dwordx4 v[178:181], v[96:97], off offset:16
	s_waitcnt vmcnt(18)
	v_mfma_f32_16x16x32_bf16 v[48:51], v[162:165], v[182:185], v[48:51]
	v_mfma_f32_16x16x32_bf16 v[28:31], v[166:169], v[182:185], v[28:31]
	v_mfma_f32_16x16x32_bf16 v[20:23], v[170:173], v[182:185], v[20:23]
	v_mfma_f32_16x16x32_bf16 v[8:11], v[174:177], v[182:185], v[8:11]
	s_waitcnt vmcnt(17)
	v_mfma_f32_16x16x32_bf16 v[32:35], v[162:165], v[186:189], v[32:35]
	v_mfma_f32_16x16x32_bf16 v[24:27], v[166:169], v[186:189], v[24:27]
	v_mfma_f32_16x16x32_bf16 v[16:19], v[170:173], v[186:189], v[16:19]
	v_mfma_f32_16x16x32_bf16 v[4:7], v[174:177], v[186:189], v[4:7]
	s_waitcnt vmcnt(16)
	v_mfma_f32_16x16x32_bf16 v[60:63], v[162:165], v[198:201], v[60:63]
	v_mfma_f32_16x16x32_bf16 v[56:59], v[166:169], v[198:201], v[56:59]
	v_mfma_f32_16x16x32_bf16 v[64:67], v[170:173], v[198:201], v[64:67]
	v_mfma_f32_16x16x32_bf16 v[52:55], v[174:177], v[198:201], v[52:55]
	s_waitcnt vmcnt(11)
	v_mfma_f32_16x16x32_bf16 v[12:15], v[218:221], v[234:237], v[12:15]
	s_waitcnt vmcnt(11)
	v_mfma_f32_16x16x32_bf16 v[36:39], v[222:225], v[234:237], v[36:39]
	s_waitcnt vmcnt(11)
	v_mfma_f32_16x16x32_bf16 v[40:43], v[226:229], v[234:237], v[40:43]
	s_waitcnt vmcnt(11)
	v_mfma_f32_16x16x32_bf16 v[44:47], v[230:233], v[234:237], v[44:47]
	s_waitcnt vmcnt(10)
	v_mfma_f32_16x16x32_bf16 v[48:51], v[218:221], v[238:241], v[48:51]
	v_mfma_f32_16x16x32_bf16 v[28:31], v[222:225], v[238:241], v[28:31]
	v_mfma_f32_16x16x32_bf16 v[20:23], v[226:229], v[238:241], v[20:23]
	v_mfma_f32_16x16x32_bf16 v[8:11], v[230:233], v[238:241], v[8:11]
	s_waitcnt vmcnt(9)
	v_mfma_f32_16x16x32_bf16 v[32:35], v[218:221], v[246:249], v[32:35]
	v_mfma_f32_16x16x32_bf16 v[24:27], v[222:225], v[246:249], v[24:27]
	v_mfma_f32_16x16x32_bf16 v[16:19], v[226:229], v[246:249], v[16:19]
	v_mfma_f32_16x16x32_bf16 v[4:7], v[230:233], v[246:249], v[4:7]
	s_waitcnt vmcnt(8)
	v_mfma_f32_16x16x32_bf16 v[60:63], v[218:221], v[146:149], v[60:63]
	v_mfma_f32_16x16x32_bf16 v[56:59], v[222:225], v[146:149], v[56:59]
	v_mfma_f32_16x16x32_bf16 v[64:67], v[226:229], v[146:149], v[64:67]
	v_mfma_f32_16x16x32_bf16 v[52:55], v[230:233], v[146:149], v[52:55]
	s_waitcnt vmcnt(3)
	v_mfma_f32_16x16x32_bf16 v[12:15], v[150:153], v[138:141], v[12:15]
	s_waitcnt vmcnt(3)
	v_mfma_f32_16x16x32_bf16 v[36:39], v[154:157], v[138:141], v[36:39]
	s_waitcnt vmcnt(3)
	v_mfma_f32_16x16x32_bf16 v[40:43], v[130:133], v[138:141], v[40:43]
	s_waitcnt vmcnt(3)
	v_mfma_f32_16x16x32_bf16 v[44:47], v[134:137], v[138:141], v[44:47]
	s_waitcnt vmcnt(2)
	v_mfma_f32_16x16x32_bf16 v[48:51], v[150:153], v[142:145], v[48:51]
	v_mfma_f32_16x16x32_bf16 v[28:31], v[154:157], v[142:145], v[28:31]
	v_mfma_f32_16x16x32_bf16 v[20:23], v[130:133], v[142:145], v[20:23]
	v_mfma_f32_16x16x32_bf16 v[8:11], v[134:137], v[142:145], v[8:11]
	s_waitcnt vmcnt(1)
	v_mfma_f32_16x16x32_bf16 v[32:35], v[150:153], v[158:161], v[32:35]
	v_mfma_f32_16x16x32_bf16 v[24:27], v[154:157], v[158:161], v[24:27]
	v_mfma_f32_16x16x32_bf16 v[16:19], v[130:133], v[158:161], v[16:19]
	v_mfma_f32_16x16x32_bf16 v[4:7], v[134:137], v[158:161], v[4:7]
	s_waitcnt vmcnt(0)
	v_mfma_f32_16x16x32_bf16 v[60:63], v[150:153], v[178:181], v[60:63]
	v_mfma_f32_16x16x32_bf16 v[56:59], v[154:157], v[178:181], v[56:59]
	v_mfma_f32_16x16x32_bf16 v[64:67], v[130:133], v[178:181], v[64:67]
	v_mfma_f32_16x16x32_bf16 v[52:55], v[134:137], v[178:181], v[52:55]
	s_branch .LBB0_711
